# v087 + WIN epilogue P stores write-through (sc1)
# baseline (speedup 1.0000x reference)
.LBB0_455:
	s_lshl_b32 s1, s0, 8
	s_cmp_lg_u32 s0, 8
	s_cselect_b32 s1, s1, 0x300
	v_lshlrev_b32_e32 v166, 3, v161
	s_or_b32 s1, s1, s15
	v_or_b32_e32 v166, s1, v166
	s_lshl_b32 s1, s62, 8
	v_cmp_eq_u32_e64 s[40:41], 0, v161
	v_add_u32_e32 v161, s1, v165
	v_lshlrev_b32_e32 v166, 1, v166
	v_lshl_add_u32 v168, v161, 12, v166
	v_mul_lo_u32 v161, v161, 20
	s_waitcnt lgkmcnt(0)
	v_pk_fma_f32 v[146:147], v[146:147], v[160:161], v[110:111] op_sel_hi:[1,0,1]
	v_pk_fma_f32 v[144:145], v[144:145], v[160:161], v[108:109] op_sel_hi:[1,0,1]
	v_pk_fma_f32 v[142:143], v[142:143], v[160:161], v[102:103] op_sel_hi:[1,0,1]
	v_pk_fma_f32 v[140:141], v[140:141], v[160:161], v[100:101] op_sel_hi:[1,0,1]
	s_cmp_lt_i32 s0, 3
	v_or_b32_e32 v167, s13, v161
	v_cvt_pk_bf16_f32 v170, v144, v145
	v_cvt_pk_bf16_f32 v171, v146, v147
	v_cvt_pk_bf16_f32 v172, v140, v141
	v_cvt_pk_bf16_f32 v173, v142, v143
	s_cselect_b64 s[44:45], -1, 0
	s_cmp_gt_i32 s0, 2
	global_store_dwordx4 v168, v[170:173], s[92:93] sc1
	s_cbranch_scc1 .LBB0_459
	v_mul_f32_e32 v145, v145, v145
	v_fmac_f32_e32 v145, v144, v144
	v_mul_f32_e32 v144, v147, v147
	v_fmac_f32_e32 v144, v146, v146
	v_mul_f32_e32 v141, v141, v141
	v_add_f32_e32 v144, v145, v144
	v_fmac_f32_e32 v141, v140, v140
	v_add_f32_e32 v140, v141, v144
	v_mul_f32_e32 v141, v143, v143
	v_fmac_f32_e32 v141, v142, v142
	v_and_b32_e32 v142, 64, v1
	v_add_f32_e32 v140, v141, v140
	v_add_u32_e32 v142, 64, v142
	v_mov_b32_e32 v141, v140
	s_nop 1
	v_permlane16_swap_b32_e32 v140, v141
	s_waitcnt lgkmcnt(0)
	v_add_f32_e32 v140, v140, v141
	v_mov_b32_e32 v141, v140
	s_nop 1
	v_permlane32_swap_b32_e32 v140, v141
	s_and_saveexec_b64 s[42:43], s[40:41]
	s_cbranch_execz .LBB0_458
	s_lshl_b32 s49, s0, 5
	v_lshl_add_u32 v142, v167, 2, s49
	s_waitcnt lgkmcnt(0)
	v_add_f32_e32 v140, v140, v141
	global_store_dword v142, v140, s[74:75]

.LBB0_459:
	s_lshl_b32 s42, s0, 1
	v_mov_b32_e32 v161, v160
	v_mov_b32_e32 v140, v160
	s_waitcnt lgkmcnt(0)
	v_mov_b32_e32 v141, v160
	s_or_b32 s49, s42, 1
	v_pk_fma_f32 v[138:139], v[138:139], v[140:141], v[96:97]
	v_pk_fma_f32 v[136:137], v[136:137], v[160:161], v[94:95]
	v_pk_fma_f32 v[134:135], v[134:135], v[140:141], v[92:93]
	v_pk_fma_f32 v[132:133], v[132:133], v[160:161], v[90:91]
	s_cmp_lt_i32 s49, 5
	v_cvt_pk_bf16_f32 v140, v136, v137
	v_cvt_pk_bf16_f32 v141, v138, v139
	v_cvt_pk_bf16_f32 v142, v132, v133
	v_cvt_pk_bf16_f32 v143, v134, v135
	v_or_b32_e32 v144, 0x100, v168
	s_cselect_b64 s[62:63], -1, 0
	s_cmp_gt_i32 s49, 4
	global_store_dwordx4 v144, v[140:143], s[92:93] sc1
	s_cbranch_scc1 .LBB0_463
	v_mul_f32_e32 v137, v137, v137
	v_fmac_f32_e32 v137, v136, v136
	v_mul_f32_e32 v136, v139, v139
	v_fmac_f32_e32 v136, v138, v138
	v_mul_f32_e32 v133, v133, v133
	v_add_f32_e32 v136, v137, v136
	v_fmac_f32_e32 v133, v132, v132
	v_add_f32_e32 v132, v133, v136
	v_mul_f32_e32 v133, v135, v135
	v_fmac_f32_e32 v133, v134, v134
	v_and_b32_e32 v134, 64, v1
	v_add_f32_e32 v132, v133, v132
	v_add_u32_e32 v134, 64, v134
	v_mov_b32_e32 v133, v132
	s_nop 1
	v_permlane16_swap_b32_e32 v132, v133
	s_waitcnt lgkmcnt(0)
	v_add_f32_e32 v132, v132, v133
	v_mov_b32_e32 v133, v132
	s_nop 1
	v_permlane32_swap_b32_e32 v132, v133
	s_and_saveexec_b64 s[42:43], s[40:41]
	s_cbranch_execz .LBB0_462
	s_lshl_b32 s55, s49, 4
	v_lshl_add_u32 v134, v167, 2, s55
	s_waitcnt lgkmcnt(0)
	v_add_f32_e32 v132, v132, v133
	global_store_dword v134, v132, s[74:75]

.LBB0_465:
	v_add_u32_e32 v133, s1, v133
	v_lshl_add_u32 v135, v133, 12, v166
	v_mul_lo_u32 v133, v133, 20
	v_or_b32_e32 v134, s13, v133
	s_waitcnt lgkmcnt(0)
	v_pk_fma_f32 v[130:131], v[130:131], v[132:133], v[110:111] op_sel_hi:[1,0,1]
	v_pk_fma_f32 v[128:129], v[128:129], v[132:133], v[108:109] op_sel_hi:[1,0,1]
	v_pk_fma_f32 v[126:127], v[126:127], v[132:133], v[102:103] op_sel_hi:[1,0,1]
	v_pk_fma_f32 v[124:125], v[124:125], v[132:133], v[100:101] op_sel_hi:[1,0,1]
	v_cndmask_b32_e64 v133, 0, 1, s[44:45]
	v_cvt_pk_bf16_f32 v136, v128, v129
	v_cvt_pk_bf16_f32 v137, v130, v131
	v_cvt_pk_bf16_f32 v138, v124, v125
	v_cvt_pk_bf16_f32 v139, v126, v127
	v_cmp_ne_u32_e64 s[42:43], 1, v133
	s_andn2_b64 vcc, exec, s[44:45]
	global_store_dwordx4 v135, v[136:139], s[92:93] sc1
	s_cbranch_vccnz .LBB0_469
	v_mul_f32_e32 v129, v129, v129
	v_fmac_f32_e32 v129, v128, v128
	v_mul_f32_e32 v128, v131, v131
	v_fmac_f32_e32 v128, v130, v130
	v_mul_f32_e32 v125, v125, v125
	v_add_f32_e32 v128, v129, v128
	v_fmac_f32_e32 v125, v124, v124
	v_add_f32_e32 v124, v125, v128
	v_mul_f32_e32 v125, v127, v127
	v_fmac_f32_e32 v125, v126, v126
	v_and_b32_e32 v126, 64, v1
	v_add_f32_e32 v124, v125, v124
	v_add_u32_e32 v126, 64, v126
	v_mov_b32_e32 v125, v124
	s_nop 1
	v_permlane16_swap_b32_e32 v124, v125
	s_waitcnt lgkmcnt(0)
	v_add_f32_e32 v124, v124, v125
	v_mov_b32_e32 v125, v124
	s_nop 1
	v_permlane32_swap_b32_e32 v124, v125
	s_and_saveexec_b64 s[44:45], s[40:41]
	s_cbranch_execz .LBB0_468
	s_lshl_b32 s55, s0, 5
	v_lshl_add_u32 v126, v134, 2, s55
	s_waitcnt lgkmcnt(0)
	v_add_f32_e32 v124, v124, v125
	global_store_dword v126, v124, s[74:75]

.LBB0_469:
	v_mov_b32_e32 v133, v132
	v_mov_b32_e32 v124, v132
	s_waitcnt lgkmcnt(0)
	v_mov_b32_e32 v125, v132
	v_pk_fma_f32 v[122:123], v[122:123], v[124:125], v[96:97]
	v_pk_fma_f32 v[120:121], v[120:121], v[132:133], v[94:95]
	v_pk_fma_f32 v[118:119], v[118:119], v[124:125], v[92:93]
	v_pk_fma_f32 v[116:117], v[116:117], v[132:133], v[90:91]
	v_cndmask_b32_e64 v129, 0, 1, s[62:63]
	v_cvt_pk_bf16_f32 v124, v120, v121
	v_cvt_pk_bf16_f32 v125, v122, v123
	v_cvt_pk_bf16_f32 v126, v116, v117
	v_cvt_pk_bf16_f32 v127, v118, v119
	v_or_b32_e32 v128, 0x100, v135
	v_cmp_ne_u32_e64 s[44:45], 1, v129
	s_andn2_b64 vcc, exec, s[62:63]
	global_store_dwordx4 v128, v[124:127], s[92:93] sc1
	s_cbranch_vccnz .LBB0_473
	v_mul_f32_e32 v121, v121, v121
	v_fmac_f32_e32 v121, v120, v120
	v_mul_f32_e32 v120, v123, v123
	v_fmac_f32_e32 v120, v122, v122
	v_mul_f32_e32 v117, v117, v117
	v_add_f32_e32 v120, v121, v120
	v_fmac_f32_e32 v117, v116, v116
	v_add_f32_e32 v116, v117, v120
	v_mul_f32_e32 v117, v119, v119
	v_fmac_f32_e32 v117, v118, v118
	v_and_b32_e32 v118, 64, v1
	v_add_f32_e32 v116, v117, v116
	v_add_u32_e32 v118, 64, v118
	v_mov_b32_e32 v117, v116
	s_nop 1
	v_permlane16_swap_b32_e32 v116, v117
	s_waitcnt lgkmcnt(0)
	v_add_f32_e32 v116, v116, v117
	v_mov_b32_e32 v117, v116
	s_nop 1
	v_permlane32_swap_b32_e32 v116, v117
	s_and_saveexec_b64 s[62:63], s[40:41]
	s_cbranch_execz .LBB0_472
	s_lshl_b32 s55, s49, 4
	v_lshl_add_u32 v118, v134, 2, s55
	s_waitcnt lgkmcnt(0)
	v_add_f32_e32 v116, v116, v117
	global_store_dword v118, v116, s[74:75]

.LBB0_475:
	v_add_u32_e32 v117, s1, v117
	v_lshl_add_u32 v119, v117, 12, v166
	v_mul_lo_u32 v117, v117, 20
	s_waitcnt lgkmcnt(0)
	v_pk_fma_f32 v[114:115], v[114:115], v[116:117], v[110:111] op_sel_hi:[1,0,1]
	v_pk_fma_f32 v[112:113], v[112:113], v[116:117], v[108:109] op_sel_hi:[1,0,1]
	v_pk_fma_f32 v[106:107], v[106:107], v[116:117], v[102:103] op_sel_hi:[1,0,1]
	v_pk_fma_f32 v[104:105], v[104:105], v[116:117], v[100:101] op_sel_hi:[1,0,1]
	v_or_b32_e32 v118, s13, v117
	v_cvt_pk_bf16_f32 v120, v112, v113
	v_cvt_pk_bf16_f32 v121, v114, v115
	v_cvt_pk_bf16_f32 v122, v104, v105
	v_cvt_pk_bf16_f32 v123, v106, v107
	s_and_b64 vcc, exec, s[42:43]
	global_store_dwordx4 v119, v[120:123], s[92:93] sc1
	s_cbranch_vccnz .LBB0_479
	v_mul_f32_e32 v113, v113, v113
	v_fmac_f32_e32 v113, v112, v112
	v_mul_f32_e32 v112, v115, v115
	v_fmac_f32_e32 v112, v114, v114
	v_mul_f32_e32 v105, v105, v105
	v_add_f32_e32 v112, v113, v112
	v_fmac_f32_e32 v105, v104, v104
	v_add_f32_e32 v104, v105, v112
	v_mul_f32_e32 v105, v107, v107
	v_fmac_f32_e32 v105, v106, v106
	v_and_b32_e32 v106, 64, v1
	v_add_f32_e32 v104, v105, v104
	v_add_u32_e32 v106, 64, v106
	v_mov_b32_e32 v105, v104
	s_nop 1
	v_permlane16_swap_b32_e32 v104, v105
	s_waitcnt lgkmcnt(0)
	v_add_f32_e32 v104, v104, v105
	v_mov_b32_e32 v105, v104
	s_nop 1
	v_permlane32_swap_b32_e32 v104, v105
	s_and_saveexec_b64 s[62:63], s[40:41]
	s_cbranch_execz .LBB0_478
	s_lshl_b32 s55, s0, 5
	v_lshl_add_u32 v106, v118, 2, s55
	s_waitcnt lgkmcnt(0)
	v_add_f32_e32 v104, v104, v105
	global_store_dword v106, v104, s[74:75]

.LBB0_479:
	v_mov_b32_e32 v117, v116
	v_mov_b32_e32 v104, v116
	s_waitcnt lgkmcnt(0)
	v_mov_b32_e32 v105, v116
	v_pk_fma_f32 v[88:89], v[88:89], v[104:105], v[96:97]
	v_pk_fma_f32 v[86:87], v[86:87], v[116:117], v[94:95]
	v_pk_fma_f32 v[84:85], v[84:85], v[104:105], v[92:93]
	v_pk_fma_f32 v[82:83], v[82:83], v[116:117], v[90:91]
	v_cvt_pk_bf16_f32 v104, v86, v87
	v_cvt_pk_bf16_f32 v105, v88, v89
	v_cvt_pk_bf16_f32 v106, v82, v83
	v_cvt_pk_bf16_f32 v107, v84, v85
	v_or_b32_e32 v112, 0x100, v119
	s_and_b64 vcc, exec, s[44:45]
	global_store_dwordx4 v112, v[104:107], s[92:93] sc1
	s_cbranch_vccnz .LBB0_483
	v_mul_f32_e32 v87, v87, v87
	v_fmac_f32_e32 v87, v86, v86
	v_mul_f32_e32 v86, v89, v89
	v_fmac_f32_e32 v86, v88, v88
	v_mul_f32_e32 v83, v83, v83
	v_add_f32_e32 v86, v87, v86
	v_fmac_f32_e32 v83, v82, v82
	v_add_f32_e32 v82, v83, v86
	v_mul_f32_e32 v83, v85, v85
	v_fmac_f32_e32 v83, v84, v84
	v_and_b32_e32 v84, 64, v1
	v_add_f32_e32 v82, v83, v82
	v_add_u32_e32 v84, 64, v84
	v_mov_b32_e32 v83, v82
	s_nop 1
	v_permlane16_swap_b32_e32 v82, v83
	s_waitcnt lgkmcnt(0)
	v_add_f32_e32 v82, v82, v83
	v_mov_b32_e32 v83, v82
	s_nop 1
	v_permlane32_swap_b32_e32 v82, v83
	s_and_saveexec_b64 s[62:63], s[40:41]
	s_cbranch_execz .LBB0_482
	s_lshl_b32 s55, s49, 4
	v_lshl_add_u32 v84, v118, 2, s55
	s_waitcnt lgkmcnt(0)
	v_add_f32_e32 v82, v82, v83
	global_store_dword v84, v82, s[74:75]

.LBB0_485:
	v_add_u32_e32 v83, s1, v83
	v_lshl_add_u32 v85, v83, 12, v166
	v_mul_lo_u32 v83, v83, 20
	s_waitcnt lgkmcnt(0)
	v_pk_fma_f32 v[80:81], v[80:81], v[82:83], v[110:111] op_sel_hi:[1,0,1]
	v_pk_fma_f32 v[78:79], v[78:79], v[82:83], v[108:109] op_sel_hi:[1,0,1]
	v_pk_fma_f32 v[76:77], v[76:77], v[82:83], v[102:103] op_sel_hi:[1,0,1]
	v_pk_fma_f32 v[74:75], v[74:75], v[82:83], v[100:101] op_sel_hi:[1,0,1]
	v_or_b32_e32 v84, s13, v83
	v_cvt_pk_bf16_f32 v86, v78, v79
	v_cvt_pk_bf16_f32 v87, v80, v81
	v_cvt_pk_bf16_f32 v88, v74, v75
	v_cvt_pk_bf16_f32 v89, v76, v77
	s_and_b64 vcc, exec, s[42:43]
	global_store_dwordx4 v85, v[86:89], s[92:93] sc1
	s_cbranch_vccnz .LBB0_489
	v_mul_f32_e32 v79, v79, v79
	v_fmac_f32_e32 v79, v78, v78
	v_mul_f32_e32 v78, v81, v81
	v_fmac_f32_e32 v78, v80, v80
	v_mul_f32_e32 v75, v75, v75
	v_add_f32_e32 v78, v79, v78
	v_fmac_f32_e32 v75, v74, v74
	v_add_f32_e32 v74, v75, v78
	v_mul_f32_e32 v75, v77, v77
	v_fmac_f32_e32 v75, v76, v76
	v_and_b32_e32 v76, 64, v1
	v_add_f32_e32 v74, v75, v74
	v_add_u32_e32 v76, 64, v76
	v_mov_b32_e32 v75, v74
	s_nop 1
	v_permlane16_swap_b32_e32 v74, v75
	s_waitcnt lgkmcnt(0)
	v_add_f32_e32 v74, v74, v75
	v_mov_b32_e32 v75, v74
	s_nop 1
	v_permlane32_swap_b32_e32 v74, v75
	s_and_saveexec_b64 s[62:63], s[40:41]
	s_cbranch_execz .LBB0_488
	s_lshl_b32 s55, s0, 5
	v_lshl_add_u32 v76, v84, 2, s55
	s_waitcnt lgkmcnt(0)
	v_add_f32_e32 v74, v74, v75
	global_store_dword v76, v74, s[74:75]

.LBB0_489:
	v_mov_b32_e32 v83, v82
	v_mov_b32_e32 v74, v82
	s_waitcnt lgkmcnt(0)
	v_mov_b32_e32 v75, v82
	v_pk_fma_f32 v[72:73], v[72:73], v[74:75], v[96:97]
	v_pk_fma_f32 v[70:71], v[70:71], v[82:83], v[94:95]
	v_pk_fma_f32 v[68:69], v[68:69], v[74:75], v[92:93]
	v_pk_fma_f32 v[66:67], v[66:67], v[82:83], v[90:91]
	v_cvt_pk_bf16_f32 v74, v70, v71
	v_cvt_pk_bf16_f32 v75, v72, v73
	v_cvt_pk_bf16_f32 v76, v66, v67
	v_cvt_pk_bf16_f32 v77, v68, v69
	v_or_b32_e32 v78, 0x100, v85
	s_and_b64 vcc, exec, s[44:45]
	global_store_dwordx4 v78, v[74:77], s[92:93] sc1
	s_cbranch_vccnz .LBB0_493
	v_mul_f32_e32 v71, v71, v71
	v_fmac_f32_e32 v71, v70, v70
	v_mul_f32_e32 v70, v73, v73
	v_fmac_f32_e32 v70, v72, v72
	v_mul_f32_e32 v67, v67, v67
	v_add_f32_e32 v70, v71, v70
	v_fmac_f32_e32 v67, v66, v66
	v_add_f32_e32 v66, v67, v70
	v_mul_f32_e32 v67, v69, v69
	v_fmac_f32_e32 v67, v68, v68
	v_and_b32_e32 v68, 64, v1
	v_add_f32_e32 v66, v67, v66
	v_add_u32_e32 v68, 64, v68
	v_mov_b32_e32 v67, v66
	s_nop 1
	v_permlane16_swap_b32_e32 v66, v67
	s_waitcnt lgkmcnt(0)
	v_add_f32_e32 v66, v66, v67
	v_mov_b32_e32 v67, v66
	s_nop 1
	v_permlane32_swap_b32_e32 v66, v67
	s_and_saveexec_b64 s[62:63], s[40:41]
	s_cbranch_execz .LBB0_492
	s_lshl_b32 s55, s49, 4
	v_lshl_add_u32 v68, v84, 2, s55
	s_waitcnt lgkmcnt(0)
	v_add_f32_e32 v66, v66, v67
	global_store_dword v68, v66, s[74:75]

.LBB0_495:
	v_add_u32_e32 v67, s1, v67
	v_lshl_add_u32 v69, v67, 12, v166
	v_mul_lo_u32 v67, v67, 20
	s_waitcnt lgkmcnt(0)
	v_pk_fma_f32 v[64:65], v[64:65], v[66:67], v[110:111] op_sel_hi:[1,0,1]
	v_pk_fma_f32 v[62:63], v[62:63], v[66:67], v[108:109] op_sel_hi:[1,0,1]
	v_pk_fma_f32 v[60:61], v[60:61], v[66:67], v[102:103] op_sel_hi:[1,0,1]
	v_pk_fma_f32 v[58:59], v[58:59], v[66:67], v[100:101] op_sel_hi:[1,0,1]
	v_or_b32_e32 v68, s13, v67
	v_cvt_pk_bf16_f32 v70, v62, v63
	v_cvt_pk_bf16_f32 v71, v64, v65
	v_cvt_pk_bf16_f32 v72, v58, v59
	v_cvt_pk_bf16_f32 v73, v60, v61
	s_and_b64 vcc, exec, s[42:43]
	global_store_dwordx4 v69, v[70:73], s[92:93] sc1
	s_cbranch_vccnz .LBB0_499
	v_mul_f32_e32 v63, v63, v63
	v_fmac_f32_e32 v63, v62, v62
	v_mul_f32_e32 v62, v65, v65
	v_fmac_f32_e32 v62, v64, v64
	v_mul_f32_e32 v59, v59, v59
	v_add_f32_e32 v62, v63, v62
	v_fmac_f32_e32 v59, v58, v58
	v_add_f32_e32 v58, v59, v62
	v_mul_f32_e32 v59, v61, v61
	v_fmac_f32_e32 v59, v60, v60
	v_and_b32_e32 v60, 64, v1
	v_add_f32_e32 v58, v59, v58
	v_add_u32_e32 v60, 64, v60
	v_mov_b32_e32 v59, v58
	s_nop 1
	v_permlane16_swap_b32_e32 v58, v59
	s_waitcnt lgkmcnt(0)
	v_add_f32_e32 v58, v58, v59
	v_mov_b32_e32 v59, v58
	s_nop 1
	v_permlane32_swap_b32_e32 v58, v59
	s_and_saveexec_b64 s[62:63], s[40:41]
	s_cbranch_execz .LBB0_498
	s_lshl_b32 s55, s0, 5
	v_lshl_add_u32 v60, v68, 2, s55
	s_waitcnt lgkmcnt(0)
	v_add_f32_e32 v58, v58, v59
	global_store_dword v60, v58, s[74:75]

.LBB0_499:
	v_mov_b32_e32 v67, v66
	v_mov_b32_e32 v58, v66
	s_waitcnt lgkmcnt(0)
	v_mov_b32_e32 v59, v66
	v_pk_fma_f32 v[56:57], v[56:57], v[58:59], v[96:97]
	v_pk_fma_f32 v[54:55], v[54:55], v[66:67], v[94:95]
	v_pk_fma_f32 v[52:53], v[52:53], v[58:59], v[92:93]
	v_pk_fma_f32 v[50:51], v[50:51], v[66:67], v[90:91]
	v_cvt_pk_bf16_f32 v58, v54, v55
	v_cvt_pk_bf16_f32 v59, v56, v57
	v_cvt_pk_bf16_f32 v60, v50, v51
	v_cvt_pk_bf16_f32 v61, v52, v53
	v_or_b32_e32 v62, 0x100, v69
	s_and_b64 vcc, exec, s[44:45]
	global_store_dwordx4 v62, v[58:61], s[92:93] sc1
	s_cbranch_vccnz .LBB0_503
	v_mul_f32_e32 v55, v55, v55
	v_fmac_f32_e32 v55, v54, v54
	v_mul_f32_e32 v54, v57, v57
	v_fmac_f32_e32 v54, v56, v56
	v_mul_f32_e32 v51, v51, v51
	v_add_f32_e32 v54, v55, v54
	v_fmac_f32_e32 v51, v50, v50
	v_add_f32_e32 v50, v51, v54
	v_mul_f32_e32 v51, v53, v53
	v_fmac_f32_e32 v51, v52, v52
	v_and_b32_e32 v52, 64, v1
	v_add_f32_e32 v50, v51, v50
	v_add_u32_e32 v52, 64, v52
	v_mov_b32_e32 v51, v50
	s_nop 1
	v_permlane16_swap_b32_e32 v50, v51
	s_waitcnt lgkmcnt(0)
	v_add_f32_e32 v50, v50, v51
	v_mov_b32_e32 v51, v50
	s_nop 1
	v_permlane32_swap_b32_e32 v50, v51
	s_and_saveexec_b64 s[62:63], s[40:41]
	s_cbranch_execz .LBB0_502
	s_lshl_b32 s55, s49, 4
	v_lshl_add_u32 v52, v68, 2, s55
	s_waitcnt lgkmcnt(0)
	v_add_f32_e32 v50, v50, v51
	global_store_dword v52, v50, s[74:75]

.LBB0_505:
	v_add_u32_e32 v51, s1, v51
	v_lshl_add_u32 v53, v51, 12, v166
	v_mul_lo_u32 v51, v51, 20
	s_waitcnt lgkmcnt(0)
	v_pk_fma_f32 v[48:49], v[48:49], v[50:51], v[110:111] op_sel_hi:[1,0,1]
	v_pk_fma_f32 v[46:47], v[46:47], v[50:51], v[108:109] op_sel_hi:[1,0,1]
	v_pk_fma_f32 v[44:45], v[44:45], v[50:51], v[102:103] op_sel_hi:[1,0,1]
	v_pk_fma_f32 v[42:43], v[42:43], v[50:51], v[100:101] op_sel_hi:[1,0,1]
	v_or_b32_e32 v52, s13, v51
	v_cvt_pk_bf16_f32 v54, v46, v47
	v_cvt_pk_bf16_f32 v55, v48, v49
	v_cvt_pk_bf16_f32 v56, v42, v43
	v_cvt_pk_bf16_f32 v57, v44, v45
	s_and_b64 vcc, exec, s[42:43]
	global_store_dwordx4 v53, v[54:57], s[92:93] sc1
	s_cbranch_vccnz .LBB0_509
	v_mul_f32_e32 v47, v47, v47
	v_fmac_f32_e32 v47, v46, v46
	v_mul_f32_e32 v46, v49, v49
	v_fmac_f32_e32 v46, v48, v48
	v_mul_f32_e32 v43, v43, v43
	v_add_f32_e32 v46, v47, v46
	v_fmac_f32_e32 v43, v42, v42
	v_add_f32_e32 v42, v43, v46
	v_mul_f32_e32 v43, v45, v45
	v_fmac_f32_e32 v43, v44, v44
	v_and_b32_e32 v44, 64, v1
	v_add_f32_e32 v42, v43, v42
	v_add_u32_e32 v44, 64, v44
	v_mov_b32_e32 v43, v42
	s_nop 1
	v_permlane16_swap_b32_e32 v42, v43
	s_waitcnt lgkmcnt(0)
	v_add_f32_e32 v42, v42, v43
	v_mov_b32_e32 v43, v42
	s_nop 1
	v_permlane32_swap_b32_e32 v42, v43
	s_and_saveexec_b64 s[62:63], s[40:41]
	s_cbranch_execz .LBB0_508
	s_lshl_b32 s55, s0, 5
	v_lshl_add_u32 v44, v52, 2, s55
	s_waitcnt lgkmcnt(0)
	v_add_f32_e32 v42, v42, v43
	global_store_dword v44, v42, s[74:75]

.LBB0_509:
	v_mov_b32_e32 v51, v50
	v_mov_b32_e32 v42, v50
	s_waitcnt lgkmcnt(0)
	v_mov_b32_e32 v43, v50
	v_pk_fma_f32 v[40:41], v[40:41], v[42:43], v[96:97]
	v_pk_fma_f32 v[38:39], v[38:39], v[50:51], v[94:95]
	v_pk_fma_f32 v[36:37], v[36:37], v[42:43], v[92:93]
	v_pk_fma_f32 v[34:35], v[34:35], v[50:51], v[90:91]
	v_cvt_pk_bf16_f32 v42, v38, v39
	v_cvt_pk_bf16_f32 v43, v40, v41
	v_cvt_pk_bf16_f32 v44, v34, v35
	v_cvt_pk_bf16_f32 v45, v36, v37
	v_or_b32_e32 v46, 0x100, v53
	s_and_b64 vcc, exec, s[44:45]
	global_store_dwordx4 v46, v[42:45], s[92:93] sc1
	s_cbranch_vccnz .LBB0_513
	v_mul_f32_e32 v39, v39, v39
	v_fmac_f32_e32 v39, v38, v38
	v_mul_f32_e32 v38, v41, v41
	v_fmac_f32_e32 v38, v40, v40
	v_mul_f32_e32 v35, v35, v35
	v_add_f32_e32 v38, v39, v38
	v_fmac_f32_e32 v35, v34, v34
	v_add_f32_e32 v34, v35, v38
	v_mul_f32_e32 v35, v37, v37
	v_fmac_f32_e32 v35, v36, v36
	v_and_b32_e32 v36, 64, v1
	v_add_f32_e32 v34, v35, v34
	v_add_u32_e32 v36, 64, v36
	v_mov_b32_e32 v35, v34
	s_nop 1
	v_permlane16_swap_b32_e32 v34, v35
	s_waitcnt lgkmcnt(0)
	v_add_f32_e32 v34, v34, v35
	v_mov_b32_e32 v35, v34
	s_nop 1
	v_permlane32_swap_b32_e32 v34, v35
	s_and_saveexec_b64 s[62:63], s[40:41]
	s_cbranch_execz .LBB0_512
	s_lshl_b32 s55, s49, 4
	v_lshl_add_u32 v36, v52, 2, s55
	s_waitcnt lgkmcnt(0)
	v_add_f32_e32 v34, v34, v35
	global_store_dword v36, v34, s[74:75]

.LBB0_515:
	v_add_u32_e32 v35, s1, v35
	v_lshl_add_u32 v37, v35, 12, v166
	v_mul_lo_u32 v35, v35, 20
	s_waitcnt lgkmcnt(0)
	v_pk_fma_f32 v[32:33], v[32:33], v[34:35], v[110:111] op_sel_hi:[1,0,1]
	v_pk_fma_f32 v[30:31], v[30:31], v[34:35], v[108:109] op_sel_hi:[1,0,1]
	v_pk_fma_f32 v[28:29], v[28:29], v[34:35], v[102:103] op_sel_hi:[1,0,1]
	v_pk_fma_f32 v[26:27], v[26:27], v[34:35], v[100:101] op_sel_hi:[1,0,1]
	v_or_b32_e32 v36, s13, v35
	v_cvt_pk_bf16_f32 v38, v30, v31
	v_cvt_pk_bf16_f32 v39, v32, v33
	v_cvt_pk_bf16_f32 v40, v26, v27
	v_cvt_pk_bf16_f32 v41, v28, v29
	s_and_b64 vcc, exec, s[42:43]
	global_store_dwordx4 v37, v[38:41], s[92:93] sc1
	s_cbranch_vccnz .LBB0_519
	v_mul_f32_e32 v31, v31, v31
	v_fmac_f32_e32 v31, v30, v30
	v_mul_f32_e32 v30, v33, v33
	v_fmac_f32_e32 v30, v32, v32
	v_mul_f32_e32 v27, v27, v27
	v_add_f32_e32 v30, v31, v30
	v_fmac_f32_e32 v27, v26, v26
	v_add_f32_e32 v26, v27, v30
	v_mul_f32_e32 v27, v29, v29
	v_fmac_f32_e32 v27, v28, v28
	v_and_b32_e32 v28, 64, v1
	v_add_f32_e32 v26, v27, v26
	v_add_u32_e32 v28, 64, v28
	v_mov_b32_e32 v27, v26
	s_nop 1
	v_permlane16_swap_b32_e32 v26, v27
	s_waitcnt lgkmcnt(0)
	v_add_f32_e32 v26, v26, v27
	v_mov_b32_e32 v27, v26
	s_nop 1
	v_permlane32_swap_b32_e32 v26, v27
	s_and_saveexec_b64 s[62:63], s[40:41]
	s_cbranch_execz .LBB0_518
	s_lshl_b32 s55, s0, 5
	v_lshl_add_u32 v28, v36, 2, s55
	s_waitcnt lgkmcnt(0)
	v_add_f32_e32 v26, v26, v27
	global_store_dword v28, v26, s[74:75]

.LBB0_519:
	v_mov_b32_e32 v35, v34
	v_mov_b32_e32 v26, v34
	s_waitcnt lgkmcnt(0)
	v_mov_b32_e32 v27, v34
	v_pk_fma_f32 v[24:25], v[24:25], v[26:27], v[96:97]
	v_pk_fma_f32 v[22:23], v[22:23], v[34:35], v[94:95]
	v_pk_fma_f32 v[20:21], v[20:21], v[26:27], v[92:93]
	v_pk_fma_f32 v[18:19], v[18:19], v[34:35], v[90:91]
	v_cvt_pk_bf16_f32 v26, v22, v23
	v_cvt_pk_bf16_f32 v27, v24, v25
	v_cvt_pk_bf16_f32 v28, v18, v19
	v_cvt_pk_bf16_f32 v29, v20, v21
	v_or_b32_e32 v30, 0x100, v37
	s_and_b64 vcc, exec, s[44:45]
	global_store_dwordx4 v30, v[26:29], s[92:93] sc1
	s_cbranch_vccnz .LBB0_523
	v_mul_f32_e32 v23, v23, v23
	v_fmac_f32_e32 v23, v22, v22
	v_mul_f32_e32 v22, v25, v25
	v_fmac_f32_e32 v22, v24, v24
	v_mul_f32_e32 v19, v19, v19
	v_add_f32_e32 v22, v23, v22
	v_fmac_f32_e32 v19, v18, v18
	v_add_f32_e32 v18, v19, v22
	v_mul_f32_e32 v19, v21, v21
	v_fmac_f32_e32 v19, v20, v20
	v_and_b32_e32 v20, 64, v1
	v_add_f32_e32 v18, v19, v18
	v_add_u32_e32 v20, 64, v20
	v_mov_b32_e32 v19, v18
	s_nop 1
	v_permlane16_swap_b32_e32 v18, v19
	s_waitcnt lgkmcnt(0)
	v_add_f32_e32 v18, v18, v19
	v_mov_b32_e32 v19, v18
	s_nop 1
	v_permlane32_swap_b32_e32 v18, v19
	s_and_saveexec_b64 s[62:63], s[40:41]
	s_cbranch_execz .LBB0_522
	s_lshl_b32 s55, s49, 4
	v_lshl_add_u32 v20, v36, 2, s55
	s_waitcnt lgkmcnt(0)
	v_add_f32_e32 v18, v18, v19
	global_store_dword v20, v18, s[74:75]

.LBB0_525:
	v_add_u32_e32 v19, s1, v19
	v_lshl_add_u32 v21, v19, 12, v166
	v_mul_lo_u32 v19, v19, 20
	s_waitcnt lgkmcnt(0)
	v_pk_fma_f32 v[16:17], v[16:17], v[18:19], v[110:111] op_sel_hi:[1,0,1]
	v_pk_fma_f32 v[14:15], v[14:15], v[18:19], v[108:109] op_sel_hi:[1,0,1]
	v_pk_fma_f32 v[12:13], v[12:13], v[18:19], v[102:103] op_sel_hi:[1,0,1]
	v_pk_fma_f32 v[10:11], v[10:11], v[18:19], v[100:101] op_sel_hi:[1,0,1]
	v_or_b32_e32 v20, s13, v19
	v_cvt_pk_bf16_f32 v22, v14, v15
	v_cvt_pk_bf16_f32 v23, v16, v17
	v_cvt_pk_bf16_f32 v24, v10, v11
	v_cvt_pk_bf16_f32 v25, v12, v13
	s_and_b64 vcc, exec, s[42:43]
	global_store_dwordx4 v21, v[22:25], s[92:93] sc1
	s_cbranch_vccnz .LBB0_529
	v_mul_f32_e32 v15, v15, v15
	v_fmac_f32_e32 v15, v14, v14
	v_mul_f32_e32 v14, v17, v17
	v_fmac_f32_e32 v14, v16, v16
	v_mul_f32_e32 v11, v11, v11
	v_add_f32_e32 v14, v15, v14
	v_fmac_f32_e32 v11, v10, v10
	v_add_f32_e32 v10, v11, v14
	v_mul_f32_e32 v11, v13, v13
	v_fmac_f32_e32 v11, v12, v12
	v_and_b32_e32 v12, 64, v1
	v_add_f32_e32 v10, v11, v10
	v_add_u32_e32 v12, 64, v12
	v_mov_b32_e32 v11, v10
	s_nop 1
	v_permlane16_swap_b32_e32 v10, v11
	s_waitcnt lgkmcnt(0)
	v_add_f32_e32 v10, v10, v11
	v_mov_b32_e32 v11, v10
	s_nop 1
	v_permlane32_swap_b32_e32 v10, v11
	s_and_saveexec_b64 s[42:43], s[40:41]
	s_cbranch_execz .LBB0_528
	s_lshl_b32 s0, s0, 5
	v_lshl_add_u32 v12, v20, 2, s0
	s_waitcnt lgkmcnt(0)
	v_add_f32_e32 v10, v10, v11
	global_store_dword v12, v10, s[74:75]

.LBB0_529:
	v_mov_b32_e32 v19, v18
	v_mov_b32_e32 v10, v18
	s_waitcnt lgkmcnt(0)
	v_mov_b32_e32 v11, v18
	v_pk_fma_f32 v[8:9], v[8:9], v[10:11], v[96:97]
	v_pk_fma_f32 v[6:7], v[6:7], v[18:19], v[94:95]
	v_pk_fma_f32 v[4:5], v[4:5], v[10:11], v[92:93]
	v_pk_fma_f32 v[2:3], v[2:3], v[18:19], v[90:91]
	v_cvt_pk_bf16_f32 v10, v6, v7
	v_cvt_pk_bf16_f32 v11, v8, v9
	v_cvt_pk_bf16_f32 v12, v2, v3
	v_cvt_pk_bf16_f32 v13, v4, v5
	v_or_b32_e32 v14, 0x100, v21
	s_and_b64 vcc, exec, s[44:45]
	global_store_dwordx4 v14, v[10:13], s[92:93] sc1
	s_cbranch_vccnz .LBB0_533
	v_mul_f32_e32 v7, v7, v7
	v_fmac_f32_e32 v7, v6, v6
	v_mul_f32_e32 v6, v9, v9
	v_fmac_f32_e32 v6, v8, v8
	v_mul_f32_e32 v3, v3, v3
	v_add_f32_e32 v6, v7, v6
	v_fmac_f32_e32 v3, v2, v2
	v_add_f32_e32 v2, v3, v6
	v_mul_f32_e32 v3, v5, v5
	v_fmac_f32_e32 v3, v4, v4
	v_and_b32_e32 v4, 64, v1
	v_add_f32_e32 v2, v3, v2
	v_add_u32_e32 v4, 64, v4
	v_mov_b32_e32 v3, v2
	s_nop 1
	v_permlane16_swap_b32_e32 v2, v3
	s_waitcnt lgkmcnt(0)
	v_add_f32_e32 v2, v2, v3
	v_mov_b32_e32 v3, v2
	s_nop 1
	v_permlane32_swap_b32_e32 v2, v3
	s_and_saveexec_b64 s[0:1], s[40:41]
	s_cbranch_execz .LBB0_532
	s_lshl_b32 s40, s49, 4
	v_lshl_add_u32 v4, v20, 2, s40
	s_waitcnt lgkmcnt(0)
	v_add_f32_e32 v2, v2, v3
	global_store_dword v4, v2, s[74:75]
